# hand-written final RMSNorm phase: 4 rows per stage with two load stages in flight, DPP wave reduction instead of ds_bpermute chain
# speedup vs baseline: 1.0004x; 1.0004x over previous
; __device__ __forceinline__ float bf_lo(unsigned w) { return __uint_as_float(w << 16); }
; __device__ __forceinline__ float bf_hi(unsigned w) { return __uint_as_float(w & 0xffff0000u); }
; __global__ void __launch_bounds__(NWAVES * 64, 2) trunk_fwd(Args args) {
;     ...
;         else {
;             const f32x4* gr = (const f32x4*)(ARGIN(I_FING) + lane * 8);
;             const f32x4 g0 = gr[0], g1 = gr[1], g2 = gr[128], g3 = gr[129];
;             for (int row0 = gw; row0 < M; row0 += 2 * NGW) {
;                 v4u h0[2], h1[2];
; #pragma unroll
;                 for (int k = 0; k < 2; ++k) { const bf16* hp = HB + (size_t)(row0 + k * NGW) * DM + lane * 8; h0[k] = *(const v4u*)(hp); h1[k] = *(const v4u*)(hp + 512); }
; #pragma unroll
;                 for (int k = 0; k < 2; ++k) { float* op = out + (size_t)(row0 + k * NGW) * DM + lane * 8;
;                     const f32x4 a0 = {bf_lo(h0[k].x), bf_hi(h0[k].x), bf_lo(h0[k].y), bf_hi(h0[k].y)}, a1 = {bf_lo(h0[k].z), bf_hi(h0[k].z), bf_lo(h0[k].w), bf_hi(h0[k].w)};
;                     const f32x4 a2 = {bf_lo(h1[k].x), bf_hi(h1[k].x), bf_lo(h1[k].y), bf_hi(h1[k].y)}, a3 = {bf_lo(h1[k].z), bf_hi(h1[k].z), bf_lo(h1[k].w), bf_hi(h1[k].w)};
;                     float sq = ((a0[0] * a0[0] + a0[1] * a0[1]) + (a0[2] * a0[2] + a0[3] * a0[3])) + ((a1[0] * a1[0] + a1[1] * a1[1]) + (a1[2] * a1[2] + a1[3] * a1[3]))
;                              + ((a2[0] * a2[0] + a2[1] * a2[1]) + (a2[2] * a2[2] + a2[3] * a2[3])) + ((a3[0] * a3[0] + a3[1] * a3[1]) + (a3[2] * a3[2] + a3[3] * a3[3]));
;                     const float r = __builtin_amdgcn_rsqf(wave_sum(sq) * (1.f / DM) + EPS);
;                     *(f32x4*)(op) = a0 * r * g0; *(f32x4*)(op + 4) = a1 * r * g1; *(f32x4*)(op + 512) = a2 * r * g2; *(f32x4*)(op + 516) = a3 * r * g3; }
;             }
.LBB0_594:
	s_cmp_gt_i32 s60, 0xffff
	s_cbranch_scc1 .LBB0_597
	s_load_dwordx2 s[4:5], s[62:63], 0x38
	v_lshlrev_b32_e32 v0, 5, v216
	v_lshlrev_b32_e32 v18, 4, v216
	v_mov_b32_e32 v19, v1
	v_lshl_add_u64 v[28:29], s[16:17], 0, v[0:1]
	v_lshl_add_u64 v[26:27], s[58:59], 0, v[18:19]
	s_waitcnt vmcnt(0) lgkmcnt(0)
	global_load_dwordx4 v[6:9], v0, s[4:5]
	global_load_dwordx4 v[2:5], v0, s[4:5] offset:16
	global_load_dwordx4 v[14:17], v0, s[4:5] offset:2048
	global_load_dwordx4 v[10:13], v0, s[4:5] offset:2064
	s_add_i32 s20, s60, 0
	s_lshl_b32 s20, s20, 11
	s_mov_b32 s21, 0
	v_lshl_add_u64 v[132:133], v[26:27], 0, s[20:21]
	global_load_dwordx4 v[32:35], v[132:133], off
	global_load_dwordx4 v[36:39], v[132:133], off offset:1024
	s_add_i32 s20, s60, 2048
	s_lshl_b32 s20, s20, 11
	s_mov_b32 s21, 0
	v_lshl_add_u64 v[132:133], v[26:27], 0, s[20:21]
	global_load_dwordx4 v[40:43], v[132:133], off
	global_load_dwordx4 v[44:47], v[132:133], off offset:1024
	s_add_i32 s20, s60, 4096
	s_lshl_b32 s20, s20, 11
	s_mov_b32 s21, 0
	v_lshl_add_u64 v[132:133], v[26:27], 0, s[20:21]
	global_load_dwordx4 v[48:51], v[132:133], off
	global_load_dwordx4 v[52:55], v[132:133], off offset:1024
	s_add_i32 s20, s60, 6144
	s_lshl_b32 s20, s20, 11
	s_mov_b32 s21, 0
	v_lshl_add_u64 v[132:133], v[26:27], 0, s[20:21]
	global_load_dwordx4 v[56:59], v[132:133], off
	global_load_dwordx4 v[60:63], v[132:133], off offset:1024
	s_add_i32 s22, s60, 0x2000
	s_add_i32 s20, s22, 0
	s_lshl_b32 s20, s20, 11
	s_mov_b32 s21, 0
	v_lshl_add_u64 v[132:133], v[26:27], 0, s[20:21]
	global_load_dwordx4 v[64:67], v[132:133], off
	global_load_dwordx4 v[68:71], v[132:133], off offset:1024
	s_add_i32 s20, s22, 2048
	s_lshl_b32 s20, s20, 11
	s_mov_b32 s21, 0
	v_lshl_add_u64 v[132:133], v[26:27], 0, s[20:21]
	global_load_dwordx4 v[72:75], v[132:133], off
	global_load_dwordx4 v[76:79], v[132:133], off offset:1024
	s_add_i32 s20, s22, 4096
	s_lshl_b32 s20, s20, 11
	s_mov_b32 s21, 0
	v_lshl_add_u64 v[132:133], v[26:27], 0, s[20:21]
	global_load_dwordx4 v[80:83], v[132:133], off
	global_load_dwordx4 v[84:87], v[132:133], off offset:1024
	s_add_i32 s20, s22, 6144
	s_lshl_b32 s20, s20, 11
	s_mov_b32 s21, 0
	v_lshl_add_u64 v[132:133], v[26:27], 0, s[20:21]
	global_load_dwordx4 v[88:91], v[132:133], off
	global_load_dwordx4 v[92:95], v[132:133], off offset:1024
	s_mov_b32 s23, 1
.Lfin_loop:
	s_cmp_eq_u32 s23, 0
	s_cbranch_scc1 .Lfin_wa24
	s_waitcnt vmcnt(8)
	s_branch .Lfin_wad
.Lfin_wa24:
	s_waitcnt vmcnt(24)
.Lfin_wad:
	s_mov_b32 s23, 0
	v_lshlrev_b32_e32 v96, 16, v32
	v_and_b32_e32 v97, 0xffff0000, v32
	v_lshlrev_b32_e32 v98, 16, v33
	v_and_b32_e32 v99, 0xffff0000, v33
	v_lshlrev_b32_e32 v100, 16, v34
	v_and_b32_e32 v101, 0xffff0000, v34
	v_lshlrev_b32_e32 v102, 16, v35
	v_and_b32_e32 v103, 0xffff0000, v35
	v_lshlrev_b32_e32 v104, 16, v36
	v_and_b32_e32 v105, 0xffff0000, v36
	v_lshlrev_b32_e32 v106, 16, v37
	v_and_b32_e32 v107, 0xffff0000, v37
	v_lshlrev_b32_e32 v108, 16, v38
	v_and_b32_e32 v109, 0xffff0000, v38
	v_lshlrev_b32_e32 v110, 16, v39
	v_and_b32_e32 v111, 0xffff0000, v39
	v_pk_mul_f32 v[128:129], v[96:97], v[96:97]
	v_pk_fma_f32 v[128:129], v[98:99], v[98:99], v[128:129]
	v_pk_fma_f32 v[128:129], v[100:101], v[100:101], v[128:129]
	v_pk_fma_f32 v[128:129], v[102:103], v[102:103], v[128:129]
	v_pk_fma_f32 v[128:129], v[104:105], v[104:105], v[128:129]
	v_pk_fma_f32 v[128:129], v[106:107], v[106:107], v[128:129]
	v_pk_fma_f32 v[128:129], v[108:109], v[108:109], v[128:129]
	v_pk_fma_f32 v[128:129], v[110:111], v[110:111], v[128:129]
	v_add_f32_e32 v128, v128, v129
	s_nop 1
	v_add_f32_dpp v128, v128, v128 quad_perm:[1,0,3,2] row_mask:0xf bank_mask:0xf
	s_nop 1
	v_add_f32_dpp v128, v128, v128 quad_perm:[2,3,0,1] row_mask:0xf bank_mask:0xf
	s_nop 1
	v_add_f32_dpp v128, v128, v128 row_half_mirror row_mask:0xf bank_mask:0xf
	s_nop 1
	v_add_f32_dpp v128, v128, v128 row_mirror row_mask:0xf bank_mask:0xf
	s_nop 1
	v_readlane_b32 s6, v128, 0
	v_readlane_b32 s7, v128, 16
	v_readlane_b32 s8, v128, 32
	v_readlane_b32 s9, v128, 48
	s_nop 1
	v_mov_b32_e32 v130, s6
	v_add_f32_e32 v130, s7, v130
	v_add_f32_e32 v130, s8, v130
	v_add_f32_e32 v130, s9, v130
	v_fmamk_f32 v130, v130, 0x3a800000, v207
	v_rsq_f32_e32 v130, v130
	s_add_i32 s20, s60, 0
	s_lshl_b32 s20, s20, 12
	s_mov_b32 s21, 0
	v_lshl_add_u64 v[134:135], v[28:29], 0, s[20:21]
	v_pk_mul_f32 v[96:97], v[96:97], v[130:131] op_sel_hi:[1,0]
	v_pk_mul_f32 v[98:99], v[98:99], v[130:131] op_sel_hi:[1,0]
	v_pk_mul_f32 v[100:101], v[100:101], v[130:131] op_sel_hi:[1,0]
	v_pk_mul_f32 v[102:103], v[102:103], v[130:131] op_sel_hi:[1,0]
	v_pk_mul_f32 v[104:105], v[104:105], v[130:131] op_sel_hi:[1,0]
	v_pk_mul_f32 v[106:107], v[106:107], v[130:131] op_sel_hi:[1,0]
	v_pk_mul_f32 v[108:109], v[108:109], v[130:131] op_sel_hi:[1,0]
	v_pk_mul_f32 v[110:111], v[110:111], v[130:131] op_sel_hi:[1,0]
	v_pk_mul_f32 v[96:97], v[96:97], v[6:7]
	v_pk_mul_f32 v[98:99], v[98:99], v[8:9]
	v_pk_mul_f32 v[100:101], v[100:101], v[2:3]
	v_pk_mul_f32 v[102:103], v[102:103], v[4:5]
	v_pk_mul_f32 v[104:105], v[104:105], v[14:15]
	v_pk_mul_f32 v[106:107], v[106:107], v[16:17]
	v_pk_mul_f32 v[108:109], v[108:109], v[10:11]
	v_pk_mul_f32 v[110:111], v[110:111], v[12:13]
	global_store_dwordx4 v[134:135], v[96:99], off
	global_store_dwordx4 v[134:135], v[100:103], off offset:16
	global_store_dwordx4 v[134:135], v[104:107], off offset:2048
	global_store_dwordx4 v[134:135], v[108:111], off offset:2064
	v_lshlrev_b32_e32 v112, 16, v40
	v_and_b32_e32 v113, 0xffff0000, v40
	v_lshlrev_b32_e32 v114, 16, v41
	v_and_b32_e32 v115, 0xffff0000, v41
	v_lshlrev_b32_e32 v116, 16, v42
	v_and_b32_e32 v117, 0xffff0000, v42
; __device__ __forceinline__ float bf_lo(unsigned w) { return __uint_as_float(w << 16); }
; __device__ __forceinline__ float bf_hi(unsigned w) { return __uint_as_float(w & 0xffff0000u); }
; __global__ void __launch_bounds__(NWAVES * 64, 2) trunk_fwd(Args args) {
;     ...
;         else {
;             const f32x4* gr = (const f32x4*)(ARGIN(I_FING) + lane * 8);
;             const f32x4 g0 = gr[0], g1 = gr[1], g2 = gr[128], g3 = gr[129];
;             for (int row0 = gw; row0 < M; row0 += 2 * NGW) {
;                 v4u h0[2], h1[2];
; #pragma unroll
;                 for (int k = 0; k < 2; ++k) { const bf16* hp = HB + (size_t)(row0 + k * NGW) * DM + lane * 8; h0[k] = *(const v4u*)(hp); h1[k] = *(const v4u*)(hp + 512); }
; #pragma unroll
;                 for (int k = 0; k < 2; ++k) { float* op = out + (size_t)(row0 + k * NGW) * DM + lane * 8;
;                     const f32x4 a0 = {bf_lo(h0[k].x), bf_hi(h0[k].x), bf_lo(h0[k].y), bf_hi(h0[k].y)}, a1 = {bf_lo(h0[k].z), bf_hi(h0[k].z), bf_lo(h0[k].w), bf_hi(h0[k].w)};
;                     const f32x4 a2 = {bf_lo(h1[k].x), bf_hi(h1[k].x), bf_lo(h1[k].y), bf_hi(h1[k].y)}, a3 = {bf_lo(h1[k].z), bf_hi(h1[k].z), bf_lo(h1[k].w), bf_hi(h1[k].w)};
;                     float sq = ((a0[0] * a0[0] + a0[1] * a0[1]) + (a0[2] * a0[2] + a0[3] * a0[3])) + ((a1[0] * a1[0] + a1[1] * a1[1]) + (a1[2] * a1[2] + a1[3] * a1[3]))
;                              + ((a2[0] * a2[0] + a2[1] * a2[1]) + (a2[2] * a2[2] + a2[3] * a2[3])) + ((a3[0] * a3[0] + a3[1] * a3[1]) + (a3[2] * a3[2] + a3[3] * a3[3]));
;                     const float r = __builtin_amdgcn_rsqf(wave_sum(sq) * (1.f / DM) + EPS);
;                     *(f32x4*)(op) = a0 * r * g0; *(f32x4*)(op + 4) = a1 * r * g1; *(f32x4*)(op + 512) = a2 * r * g2; *(f32x4*)(op + 516) = a3 * r * g3; }
;             }
	v_lshlrev_b32_e32 v118, 16, v43
	v_and_b32_e32 v119, 0xffff0000, v43
	v_lshlrev_b32_e32 v120, 16, v44
	v_and_b32_e32 v121, 0xffff0000, v44
	v_lshlrev_b32_e32 v122, 16, v45
	v_and_b32_e32 v123, 0xffff0000, v45
	v_lshlrev_b32_e32 v124, 16, v46
	v_and_b32_e32 v125, 0xffff0000, v46
	v_lshlrev_b32_e32 v126, 16, v47
	v_and_b32_e32 v127, 0xffff0000, v47
	v_pk_mul_f32 v[128:129], v[112:113], v[112:113]
	v_pk_fma_f32 v[128:129], v[114:115], v[114:115], v[128:129]
	v_pk_fma_f32 v[128:129], v[116:117], v[116:117], v[128:129]
	v_pk_fma_f32 v[128:129], v[118:119], v[118:119], v[128:129]
	v_pk_fma_f32 v[128:129], v[120:121], v[120:121], v[128:129]
	v_pk_fma_f32 v[128:129], v[122:123], v[122:123], v[128:129]
	v_pk_fma_f32 v[128:129], v[124:125], v[124:125], v[128:129]
	v_pk_fma_f32 v[128:129], v[126:127], v[126:127], v[128:129]
	v_add_f32_e32 v128, v128, v129
	s_nop 1
	v_add_f32_dpp v128, v128, v128 quad_perm:[1,0,3,2] row_mask:0xf bank_mask:0xf
	s_nop 1
	v_add_f32_dpp v128, v128, v128 quad_perm:[2,3,0,1] row_mask:0xf bank_mask:0xf
	s_nop 1
	v_add_f32_dpp v128, v128, v128 row_half_mirror row_mask:0xf bank_mask:0xf
	s_nop 1
	v_add_f32_dpp v128, v128, v128 row_mirror row_mask:0xf bank_mask:0xf
	s_nop 1
	v_readlane_b32 s6, v128, 0
	v_readlane_b32 s7, v128, 16
	v_readlane_b32 s8, v128, 32
	v_readlane_b32 s9, v128, 48
	s_nop 1
	v_mov_b32_e32 v130, s6
	v_add_f32_e32 v130, s7, v130
	v_add_f32_e32 v130, s8, v130
	v_add_f32_e32 v130, s9, v130
	v_fmamk_f32 v130, v130, 0x3a800000, v207
	v_rsq_f32_e32 v130, v130
	s_add_i32 s20, s60, 2048
	s_lshl_b32 s20, s20, 12
	s_mov_b32 s21, 0
	v_lshl_add_u64 v[134:135], v[28:29], 0, s[20:21]
	v_pk_mul_f32 v[112:113], v[112:113], v[130:131] op_sel_hi:[1,0]
	v_pk_mul_f32 v[114:115], v[114:115], v[130:131] op_sel_hi:[1,0]
	v_pk_mul_f32 v[116:117], v[116:117], v[130:131] op_sel_hi:[1,0]
	v_pk_mul_f32 v[118:119], v[118:119], v[130:131] op_sel_hi:[1,0]
	v_pk_mul_f32 v[120:121], v[120:121], v[130:131] op_sel_hi:[1,0]
	v_pk_mul_f32 v[122:123], v[122:123], v[130:131] op_sel_hi:[1,0]
	v_pk_mul_f32 v[124:125], v[124:125], v[130:131] op_sel_hi:[1,0]
	v_pk_mul_f32 v[126:127], v[126:127], v[130:131] op_sel_hi:[1,0]
	v_pk_mul_f32 v[112:113], v[112:113], v[6:7]
	v_pk_mul_f32 v[114:115], v[114:115], v[8:9]
	v_pk_mul_f32 v[116:117], v[116:117], v[2:3]
	v_pk_mul_f32 v[118:119], v[118:119], v[4:5]
	v_pk_mul_f32 v[120:121], v[120:121], v[14:15]
	v_pk_mul_f32 v[122:123], v[122:123], v[16:17]
	v_pk_mul_f32 v[124:125], v[124:125], v[10:11]
	v_pk_mul_f32 v[126:127], v[126:127], v[12:13]
	global_store_dwordx4 v[134:135], v[112:115], off
	global_store_dwordx4 v[134:135], v[116:119], off offset:16
	global_store_dwordx4 v[134:135], v[120:123], off offset:2048
	global_store_dwordx4 v[134:135], v[124:127], off offset:2064
	v_lshlrev_b32_e32 v96, 16, v48
	v_and_b32_e32 v97, 0xffff0000, v48
	v_lshlrev_b32_e32 v98, 16, v49
	v_and_b32_e32 v99, 0xffff0000, v49
	v_lshlrev_b32_e32 v100, 16, v50
	v_and_b32_e32 v101, 0xffff0000, v50
	v_lshlrev_b32_e32 v102, 16, v51
	v_and_b32_e32 v103, 0xffff0000, v51
	v_lshlrev_b32_e32 v104, 16, v52
	v_and_b32_e32 v105, 0xffff0000, v52
	v_lshlrev_b32_e32 v106, 16, v53
	v_and_b32_e32 v107, 0xffff0000, v53
	v_lshlrev_b32_e32 v108, 16, v54
	v_and_b32_e32 v109, 0xffff0000, v54
	v_lshlrev_b32_e32 v110, 16, v55
	v_and_b32_e32 v111, 0xffff0000, v55
	v_pk_mul_f32 v[128:129], v[96:97], v[96:97]
	v_pk_fma_f32 v[128:129], v[98:99], v[98:99], v[128:129]
	v_pk_fma_f32 v[128:129], v[100:101], v[100:101], v[128:129]
	v_pk_fma_f32 v[128:129], v[102:103], v[102:103], v[128:129]
	v_pk_fma_f32 v[128:129], v[104:105], v[104:105], v[128:129]
	v_pk_fma_f32 v[128:129], v[106:107], v[106:107], v[128:129]
	v_pk_fma_f32 v[128:129], v[108:109], v[108:109], v[128:129]
	v_pk_fma_f32 v[128:129], v[110:111], v[110:111], v[128:129]
	v_add_f32_e32 v128, v128, v129
	s_nop 1
	v_add_f32_dpp v128, v128, v128 quad_perm:[1,0,3,2] row_mask:0xf bank_mask:0xf
	s_nop 1
	v_add_f32_dpp v128, v128, v128 quad_perm:[2,3,0,1] row_mask:0xf bank_mask:0xf
	s_nop 1
	v_add_f32_dpp v128, v128, v128 row_half_mirror row_mask:0xf bank_mask:0xf
	s_nop 1
	v_add_f32_dpp v128, v128, v128 row_mirror row_mask:0xf bank_mask:0xf
	s_nop 1
	v_readlane_b32 s6, v128, 0
	v_readlane_b32 s7, v128, 16
	v_readlane_b32 s8, v128, 32
	v_readlane_b32 s9, v128, 48
	s_nop 1
	v_mov_b32_e32 v130, s6
	v_add_f32_e32 v130, s7, v130
	v_add_f32_e32 v130, s8, v130
	v_add_f32_e32 v130, s9, v130
	v_fmamk_f32 v130, v130, 0x3a800000, v207
	v_rsq_f32_e32 v130, v130
	s_add_i32 s20, s60, 4096
	s_lshl_b32 s20, s20, 12
	s_mov_b32 s21, 0
	v_lshl_add_u64 v[134:135], v[28:29], 0, s[20:21]
	v_pk_mul_f32 v[96:97], v[96:97], v[130:131] op_sel_hi:[1,0]
	v_pk_mul_f32 v[98:99], v[98:99], v[130:131] op_sel_hi:[1,0]
	v_pk_mul_f32 v[100:101], v[100:101], v[130:131] op_sel_hi:[1,0]
	v_pk_mul_f32 v[102:103], v[102:103], v[130:131] op_sel_hi:[1,0]
	v_pk_mul_f32 v[104:105], v[104:105], v[130:131] op_sel_hi:[1,0]
	v_pk_mul_f32 v[106:107], v[106:107], v[130:131] op_sel_hi:[1,0]
	v_pk_mul_f32 v[108:109], v[108:109], v[130:131] op_sel_hi:[1,0]
	v_pk_mul_f32 v[110:111], v[110:111], v[130:131] op_sel_hi:[1,0]
	v_pk_mul_f32 v[96:97], v[96:97], v[6:7]
	v_pk_mul_f32 v[98:99], v[98:99], v[8:9]
	v_pk_mul_f32 v[100:101], v[100:101], v[2:3]
	v_pk_mul_f32 v[102:103], v[102:103], v[4:5]
	v_pk_mul_f32 v[104:105], v[104:105], v[14:15]
	v_pk_mul_f32 v[106:107], v[106:107], v[16:17]
	v_pk_mul_f32 v[108:109], v[108:109], v[10:11]
	v_pk_mul_f32 v[110:111], v[110:111], v[12:13]
	global_store_dwordx4 v[134:135], v[96:99], off
	global_store_dwordx4 v[134:135], v[100:103], off offset:16
	global_store_dwordx4 v[134:135], v[104:107], off offset:2048
; __device__ __forceinline__ float bf_lo(unsigned w) { return __uint_as_float(w << 16); }
; __device__ __forceinline__ float bf_hi(unsigned w) { return __uint_as_float(w & 0xffff0000u); }
; __global__ void __launch_bounds__(NWAVES * 64, 2) trunk_fwd(Args args) {
;     ...
;         else {
;             const f32x4* gr = (const f32x4*)(ARGIN(I_FING) + lane * 8);
;             const f32x4 g0 = gr[0], g1 = gr[1], g2 = gr[128], g3 = gr[129];
;             for (int row0 = gw; row0 < M; row0 += 2 * NGW) {
;                 v4u h0[2], h1[2];
; #pragma unroll
;                 for (int k = 0; k < 2; ++k) { const bf16* hp = HB + (size_t)(row0 + k * NGW) * DM + lane * 8; h0[k] = *(const v4u*)(hp); h1[k] = *(const v4u*)(hp + 512); }
; #pragma unroll
;                 for (int k = 0; k < 2; ++k) { float* op = out + (size_t)(row0 + k * NGW) * DM + lane * 8;
;                     const f32x4 a0 = {bf_lo(h0[k].x), bf_hi(h0[k].x), bf_lo(h0[k].y), bf_hi(h0[k].y)}, a1 = {bf_lo(h0[k].z), bf_hi(h0[k].z), bf_lo(h0[k].w), bf_hi(h0[k].w)};
;                     const f32x4 a2 = {bf_lo(h1[k].x), bf_hi(h1[k].x), bf_lo(h1[k].y), bf_hi(h1[k].y)}, a3 = {bf_lo(h1[k].z), bf_hi(h1[k].z), bf_lo(h1[k].w), bf_hi(h1[k].w)};
;                     float sq = ((a0[0] * a0[0] + a0[1] * a0[1]) + (a0[2] * a0[2] + a0[3] * a0[3])) + ((a1[0] * a1[0] + a1[1] * a1[1]) + (a1[2] * a1[2] + a1[3] * a1[3]))
;                              + ((a2[0] * a2[0] + a2[1] * a2[1]) + (a2[2] * a2[2] + a2[3] * a2[3])) + ((a3[0] * a3[0] + a3[1] * a3[1]) + (a3[2] * a3[2] + a3[3] * a3[3]));
;                     const float r = __builtin_amdgcn_rsqf(wave_sum(sq) * (1.f / DM) + EPS);
;                     *(f32x4*)(op) = a0 * r * g0; *(f32x4*)(op + 4) = a1 * r * g1; *(f32x4*)(op + 512) = a2 * r * g2; *(f32x4*)(op + 516) = a3 * r * g3; }
;             }
	global_store_dwordx4 v[134:135], v[108:111], off offset:2064
	v_lshlrev_b32_e32 v112, 16, v56
	v_and_b32_e32 v113, 0xffff0000, v56
	v_lshlrev_b32_e32 v114, 16, v57
	v_and_b32_e32 v115, 0xffff0000, v57
	v_lshlrev_b32_e32 v116, 16, v58
	v_and_b32_e32 v117, 0xffff0000, v58
	v_lshlrev_b32_e32 v118, 16, v59
	v_and_b32_e32 v119, 0xffff0000, v59
	v_lshlrev_b32_e32 v120, 16, v60
	v_and_b32_e32 v121, 0xffff0000, v60
	v_lshlrev_b32_e32 v122, 16, v61
	v_and_b32_e32 v123, 0xffff0000, v61
	v_lshlrev_b32_e32 v124, 16, v62
	v_and_b32_e32 v125, 0xffff0000, v62
	v_lshlrev_b32_e32 v126, 16, v63
	v_and_b32_e32 v127, 0xffff0000, v63
	v_pk_mul_f32 v[128:129], v[112:113], v[112:113]
	v_pk_fma_f32 v[128:129], v[114:115], v[114:115], v[128:129]
	v_pk_fma_f32 v[128:129], v[116:117], v[116:117], v[128:129]
	v_pk_fma_f32 v[128:129], v[118:119], v[118:119], v[128:129]
	v_pk_fma_f32 v[128:129], v[120:121], v[120:121], v[128:129]
	v_pk_fma_f32 v[128:129], v[122:123], v[122:123], v[128:129]
	v_pk_fma_f32 v[128:129], v[124:125], v[124:125], v[128:129]
	v_pk_fma_f32 v[128:129], v[126:127], v[126:127], v[128:129]
	v_add_f32_e32 v128, v128, v129
	s_nop 1
	v_add_f32_dpp v128, v128, v128 quad_perm:[1,0,3,2] row_mask:0xf bank_mask:0xf
	s_nop 1
	v_add_f32_dpp v128, v128, v128 quad_perm:[2,3,0,1] row_mask:0xf bank_mask:0xf
	s_nop 1
	v_add_f32_dpp v128, v128, v128 row_half_mirror row_mask:0xf bank_mask:0xf
	s_nop 1
	v_add_f32_dpp v128, v128, v128 row_mirror row_mask:0xf bank_mask:0xf
	s_nop 1
	v_readlane_b32 s6, v128, 0
	v_readlane_b32 s7, v128, 16
	v_readlane_b32 s8, v128, 32
	v_readlane_b32 s9, v128, 48
	s_nop 1
	v_mov_b32_e32 v130, s6
	v_add_f32_e32 v130, s7, v130
	v_add_f32_e32 v130, s8, v130
	v_add_f32_e32 v130, s9, v130
	v_fmamk_f32 v130, v130, 0x3a800000, v207
	v_rsq_f32_e32 v130, v130
	s_add_i32 s20, s60, 6144
	s_lshl_b32 s20, s20, 12
	s_mov_b32 s21, 0
	v_lshl_add_u64 v[134:135], v[28:29], 0, s[20:21]
	v_pk_mul_f32 v[112:113], v[112:113], v[130:131] op_sel_hi:[1,0]
	v_pk_mul_f32 v[114:115], v[114:115], v[130:131] op_sel_hi:[1,0]
	v_pk_mul_f32 v[116:117], v[116:117], v[130:131] op_sel_hi:[1,0]
	v_pk_mul_f32 v[118:119], v[118:119], v[130:131] op_sel_hi:[1,0]
	v_pk_mul_f32 v[120:121], v[120:121], v[130:131] op_sel_hi:[1,0]
	v_pk_mul_f32 v[122:123], v[122:123], v[130:131] op_sel_hi:[1,0]
	v_pk_mul_f32 v[124:125], v[124:125], v[130:131] op_sel_hi:[1,0]
	v_pk_mul_f32 v[126:127], v[126:127], v[130:131] op_sel_hi:[1,0]
	v_pk_mul_f32 v[112:113], v[112:113], v[6:7]
	v_pk_mul_f32 v[114:115], v[114:115], v[8:9]
	v_pk_mul_f32 v[116:117], v[116:117], v[2:3]
	v_pk_mul_f32 v[118:119], v[118:119], v[4:5]
	v_pk_mul_f32 v[120:121], v[120:121], v[14:15]
	v_pk_mul_f32 v[122:123], v[122:123], v[16:17]
	v_pk_mul_f32 v[124:125], v[124:125], v[10:11]
	v_pk_mul_f32 v[126:127], v[126:127], v[12:13]
	global_store_dwordx4 v[134:135], v[112:115], off
	global_store_dwordx4 v[134:135], v[116:119], off offset:16
	global_store_dwordx4 v[134:135], v[120:123], off offset:2048
	global_store_dwordx4 v[134:135], v[124:127], off offset:2064
	s_add_i32 s22, s60, 0x4000
	s_cmp_lt_u32 s22, 0x10000
	s_cselect_b32 s24, 1, 0
	s_cbranch_scc0 .Lfin_skipA
	s_add_i32 s20, s22, 0
	s_lshl_b32 s20, s20, 11
	s_mov_b32 s21, 0
	v_lshl_add_u64 v[132:133], v[26:27], 0, s[20:21]
	global_load_dwordx4 v[32:35], v[132:133], off
	global_load_dwordx4 v[36:39], v[132:133], off offset:1024
	s_add_i32 s20, s22, 2048
	s_lshl_b32 s20, s20, 11
	s_mov_b32 s21, 0
	v_lshl_add_u64 v[132:133], v[26:27], 0, s[20:21]
	global_load_dwordx4 v[40:43], v[132:133], off
	global_load_dwordx4 v[44:47], v[132:133], off offset:1024
	s_add_i32 s20, s22, 4096
	s_lshl_b32 s20, s20, 11
	s_mov_b32 s21, 0
	v_lshl_add_u64 v[132:133], v[26:27], 0, s[20:21]
	global_load_dwordx4 v[48:51], v[132:133], off
	global_load_dwordx4 v[52:55], v[132:133], off offset:1024
	s_add_i32 s20, s22, 6144
	s_lshl_b32 s20, s20, 11
	s_mov_b32 s21, 0
	v_lshl_add_u64 v[132:133], v[26:27], 0, s[20:21]
	global_load_dwordx4 v[56:59], v[132:133], off
	global_load_dwordx4 v[60:63], v[132:133], off offset:1024
.Lfin_skipA:
	s_cmp_eq_u32 s24, 0
	s_cbranch_scc1 .Lfin_wb16
	s_waitcnt vmcnt(24)
	s_branch .Lfin_wbd
.Lfin_wb16:
	s_waitcnt vmcnt(16)
.Lfin_wbd:
	s_add_i32 s25, s60, 0x2000
	v_lshlrev_b32_e32 v96, 16, v64
	v_and_b32_e32 v97, 0xffff0000, v64
	v_lshlrev_b32_e32 v98, 16, v65
	v_and_b32_e32 v99, 0xffff0000, v65
	v_lshlrev_b32_e32 v100, 16, v66
	v_and_b32_e32 v101, 0xffff0000, v66
	v_lshlrev_b32_e32 v102, 16, v67
	v_and_b32_e32 v103, 0xffff0000, v67
	v_lshlrev_b32_e32 v104, 16, v68
	v_and_b32_e32 v105, 0xffff0000, v68
	v_lshlrev_b32_e32 v106, 16, v69
	v_and_b32_e32 v107, 0xffff0000, v69
	v_lshlrev_b32_e32 v108, 16, v70
	v_and_b32_e32 v109, 0xffff0000, v70
	v_lshlrev_b32_e32 v110, 16, v71
	v_and_b32_e32 v111, 0xffff0000, v71
	v_pk_mul_f32 v[128:129], v[96:97], v[96:97]
	v_pk_fma_f32 v[128:129], v[98:99], v[98:99], v[128:129]
	v_pk_fma_f32 v[128:129], v[100:101], v[100:101], v[128:129]
	v_pk_fma_f32 v[128:129], v[102:103], v[102:103], v[128:129]
	v_pk_fma_f32 v[128:129], v[104:105], v[104:105], v[128:129]
	v_pk_fma_f32 v[128:129], v[106:107], v[106:107], v[128:129]
	v_pk_fma_f32 v[128:129], v[108:109], v[108:109], v[128:129]
	v_pk_fma_f32 v[128:129], v[110:111], v[110:111], v[128:129]
	v_add_f32_e32 v128, v128, v129
	s_nop 1
	v_add_f32_dpp v128, v128, v128 quad_perm:[1,0,3,2] row_mask:0xf bank_mask:0xf
	s_nop 1
	v_add_f32_dpp v128, v128, v128 quad_perm:[2,3,0,1] row_mask:0xf bank_mask:0xf
	s_nop 1
	v_add_f32_dpp v128, v128, v128 row_half_mirror row_mask:0xf bank_mask:0xf
	s_nop 1
	v_add_f32_dpp v128, v128, v128 row_mirror row_mask:0xf bank_mask:0xf
	s_nop 1
	v_readlane_b32 s6, v128, 0
; __device__ __forceinline__ float bf_lo(unsigned w) { return __uint_as_float(w << 16); }
; __device__ __forceinline__ float bf_hi(unsigned w) { return __uint_as_float(w & 0xffff0000u); }
; __global__ void __launch_bounds__(NWAVES * 64, 2) trunk_fwd(Args args) {
;     ...
;         else {
;             const f32x4* gr = (const f32x4*)(ARGIN(I_FING) + lane * 8);
;             const f32x4 g0 = gr[0], g1 = gr[1], g2 = gr[128], g3 = gr[129];
;             for (int row0 = gw; row0 < M; row0 += 2 * NGW) {
;                 v4u h0[2], h1[2];
; #pragma unroll
;                 for (int k = 0; k < 2; ++k) { const bf16* hp = HB + (size_t)(row0 + k * NGW) * DM + lane * 8; h0[k] = *(const v4u*)(hp); h1[k] = *(const v4u*)(hp + 512); }
; #pragma unroll
;                 for (int k = 0; k < 2; ++k) { float* op = out + (size_t)(row0 + k * NGW) * DM + lane * 8;
;                     const f32x4 a0 = {bf_lo(h0[k].x), bf_hi(h0[k].x), bf_lo(h0[k].y), bf_hi(h0[k].y)}, a1 = {bf_lo(h0[k].z), bf_hi(h0[k].z), bf_lo(h0[k].w), bf_hi(h0[k].w)};
;                     const f32x4 a2 = {bf_lo(h1[k].x), bf_hi(h1[k].x), bf_lo(h1[k].y), bf_hi(h1[k].y)}, a3 = {bf_lo(h1[k].z), bf_hi(h1[k].z), bf_lo(h1[k].w), bf_hi(h1[k].w)};
;                     float sq = ((a0[0] * a0[0] + a0[1] * a0[1]) + (a0[2] * a0[2] + a0[3] * a0[3])) + ((a1[0] * a1[0] + a1[1] * a1[1]) + (a1[2] * a1[2] + a1[3] * a1[3]))
;                              + ((a2[0] * a2[0] + a2[1] * a2[1]) + (a2[2] * a2[2] + a2[3] * a2[3])) + ((a3[0] * a3[0] + a3[1] * a3[1]) + (a3[2] * a3[2] + a3[3] * a3[3]));
;                     const float r = __builtin_amdgcn_rsqf(wave_sum(sq) * (1.f / DM) + EPS);
;                     *(f32x4*)(op) = a0 * r * g0; *(f32x4*)(op + 4) = a1 * r * g1; *(f32x4*)(op + 512) = a2 * r * g2; *(f32x4*)(op + 516) = a3 * r * g3; }
;             }
	v_readlane_b32 s7, v128, 16
	v_readlane_b32 s8, v128, 32
	v_readlane_b32 s9, v128, 48
	s_nop 1
	v_mov_b32_e32 v130, s6
	v_add_f32_e32 v130, s7, v130
	v_add_f32_e32 v130, s8, v130
	v_add_f32_e32 v130, s9, v130
	v_fmamk_f32 v130, v130, 0x3a800000, v207
	v_rsq_f32_e32 v130, v130
	s_add_i32 s20, s25, 0
	s_lshl_b32 s20, s20, 12
	s_mov_b32 s21, 0
	v_lshl_add_u64 v[134:135], v[28:29], 0, s[20:21]
	v_pk_mul_f32 v[96:97], v[96:97], v[130:131] op_sel_hi:[1,0]
	v_pk_mul_f32 v[98:99], v[98:99], v[130:131] op_sel_hi:[1,0]
	v_pk_mul_f32 v[100:101], v[100:101], v[130:131] op_sel_hi:[1,0]
	v_pk_mul_f32 v[102:103], v[102:103], v[130:131] op_sel_hi:[1,0]
	v_pk_mul_f32 v[104:105], v[104:105], v[130:131] op_sel_hi:[1,0]
	v_pk_mul_f32 v[106:107], v[106:107], v[130:131] op_sel_hi:[1,0]
	v_pk_mul_f32 v[108:109], v[108:109], v[130:131] op_sel_hi:[1,0]
	v_pk_mul_f32 v[110:111], v[110:111], v[130:131] op_sel_hi:[1,0]
	v_pk_mul_f32 v[96:97], v[96:97], v[6:7]
	v_pk_mul_f32 v[98:99], v[98:99], v[8:9]
	v_pk_mul_f32 v[100:101], v[100:101], v[2:3]
	v_pk_mul_f32 v[102:103], v[102:103], v[4:5]
	v_pk_mul_f32 v[104:105], v[104:105], v[14:15]
	v_pk_mul_f32 v[106:107], v[106:107], v[16:17]
	v_pk_mul_f32 v[108:109], v[108:109], v[10:11]
	v_pk_mul_f32 v[110:111], v[110:111], v[12:13]
	global_store_dwordx4 v[134:135], v[96:99], off
	global_store_dwordx4 v[134:135], v[100:103], off offset:16
	global_store_dwordx4 v[134:135], v[104:107], off offset:2048
	global_store_dwordx4 v[134:135], v[108:111], off offset:2064
	v_lshlrev_b32_e32 v112, 16, v72
	v_and_b32_e32 v113, 0xffff0000, v72
	v_lshlrev_b32_e32 v114, 16, v73
	v_and_b32_e32 v115, 0xffff0000, v73
	v_lshlrev_b32_e32 v116, 16, v74
	v_and_b32_e32 v117, 0xffff0000, v74
	v_lshlrev_b32_e32 v118, 16, v75
	v_and_b32_e32 v119, 0xffff0000, v75
	v_lshlrev_b32_e32 v120, 16, v76
	v_and_b32_e32 v121, 0xffff0000, v76
	v_lshlrev_b32_e32 v122, 16, v77
	v_and_b32_e32 v123, 0xffff0000, v77
	v_lshlrev_b32_e32 v124, 16, v78
	v_and_b32_e32 v125, 0xffff0000, v78
	v_lshlrev_b32_e32 v126, 16, v79
	v_and_b32_e32 v127, 0xffff0000, v79
	v_pk_mul_f32 v[128:129], v[112:113], v[112:113]
	v_pk_fma_f32 v[128:129], v[114:115], v[114:115], v[128:129]
	v_pk_fma_f32 v[128:129], v[116:117], v[116:117], v[128:129]
	v_pk_fma_f32 v[128:129], v[118:119], v[118:119], v[128:129]
	v_pk_fma_f32 v[128:129], v[120:121], v[120:121], v[128:129]
	v_pk_fma_f32 v[128:129], v[122:123], v[122:123], v[128:129]
	v_pk_fma_f32 v[128:129], v[124:125], v[124:125], v[128:129]
	v_pk_fma_f32 v[128:129], v[126:127], v[126:127], v[128:129]
	v_add_f32_e32 v128, v128, v129
	s_nop 1
	v_add_f32_dpp v128, v128, v128 quad_perm:[1,0,3,2] row_mask:0xf bank_mask:0xf
	s_nop 1
	v_add_f32_dpp v128, v128, v128 quad_perm:[2,3,0,1] row_mask:0xf bank_mask:0xf
	s_nop 1
	v_add_f32_dpp v128, v128, v128 row_half_mirror row_mask:0xf bank_mask:0xf
	s_nop 1
	v_add_f32_dpp v128, v128, v128 row_mirror row_mask:0xf bank_mask:0xf
	s_nop 1
	v_readlane_b32 s6, v128, 0
	v_readlane_b32 s7, v128, 16
	v_readlane_b32 s8, v128, 32
	v_readlane_b32 s9, v128, 48
	s_nop 1
	v_mov_b32_e32 v130, s6
	v_add_f32_e32 v130, s7, v130
	v_add_f32_e32 v130, s8, v130
	v_add_f32_e32 v130, s9, v130
	v_fmamk_f32 v130, v130, 0x3a800000, v207
	v_rsq_f32_e32 v130, v130
	s_add_i32 s20, s25, 2048
	s_lshl_b32 s20, s20, 12
	s_mov_b32 s21, 0
	v_lshl_add_u64 v[134:135], v[28:29], 0, s[20:21]
	v_pk_mul_f32 v[112:113], v[112:113], v[130:131] op_sel_hi:[1,0]
	v_pk_mul_f32 v[114:115], v[114:115], v[130:131] op_sel_hi:[1,0]
	v_pk_mul_f32 v[116:117], v[116:117], v[130:131] op_sel_hi:[1,0]
	v_pk_mul_f32 v[118:119], v[118:119], v[130:131] op_sel_hi:[1,0]
	v_pk_mul_f32 v[120:121], v[120:121], v[130:131] op_sel_hi:[1,0]
	v_pk_mul_f32 v[122:123], v[122:123], v[130:131] op_sel_hi:[1,0]
	v_pk_mul_f32 v[124:125], v[124:125], v[130:131] op_sel_hi:[1,0]
	v_pk_mul_f32 v[126:127], v[126:127], v[130:131] op_sel_hi:[1,0]
	v_pk_mul_f32 v[112:113], v[112:113], v[6:7]
	v_pk_mul_f32 v[114:115], v[114:115], v[8:9]
	v_pk_mul_f32 v[116:117], v[116:117], v[2:3]
	v_pk_mul_f32 v[118:119], v[118:119], v[4:5]
	v_pk_mul_f32 v[120:121], v[120:121], v[14:15]
	v_pk_mul_f32 v[122:123], v[122:123], v[16:17]
	v_pk_mul_f32 v[124:125], v[124:125], v[10:11]
	v_pk_mul_f32 v[126:127], v[126:127], v[12:13]
	global_store_dwordx4 v[134:135], v[112:115], off
	global_store_dwordx4 v[134:135], v[116:119], off offset:16
	global_store_dwordx4 v[134:135], v[120:123], off offset:2048
	global_store_dwordx4 v[134:135], v[124:127], off offset:2064
	v_lshlrev_b32_e32 v96, 16, v80
	v_and_b32_e32 v97, 0xffff0000, v80
	v_lshlrev_b32_e32 v98, 16, v81
	v_and_b32_e32 v99, 0xffff0000, v81
	v_lshlrev_b32_e32 v100, 16, v82
	v_and_b32_e32 v101, 0xffff0000, v82
	v_lshlrev_b32_e32 v102, 16, v83
	v_and_b32_e32 v103, 0xffff0000, v83
	v_lshlrev_b32_e32 v104, 16, v84
	v_and_b32_e32 v105, 0xffff0000, v84
	v_lshlrev_b32_e32 v106, 16, v85
	v_and_b32_e32 v107, 0xffff0000, v85
	v_lshlrev_b32_e32 v108, 16, v86
	v_and_b32_e32 v109, 0xffff0000, v86
	v_lshlrev_b32_e32 v110, 16, v87
	v_and_b32_e32 v111, 0xffff0000, v87
	v_pk_mul_f32 v[128:129], v[96:97], v[96:97]
	v_pk_fma_f32 v[128:129], v[98:99], v[98:99], v[128:129]
	v_pk_fma_f32 v[128:129], v[100:101], v[100:101], v[128:129]
	v_pk_fma_f32 v[128:129], v[102:103], v[102:103], v[128:129]
	v_pk_fma_f32 v[128:129], v[104:105], v[104:105], v[128:129]
	v_pk_fma_f32 v[128:129], v[106:107], v[106:107], v[128:129]
	v_pk_fma_f32 v[128:129], v[108:109], v[108:109], v[128:129]
	v_pk_fma_f32 v[128:129], v[110:111], v[110:111], v[128:129]
	v_add_f32_e32 v128, v128, v129
	s_nop 1
	v_add_f32_dpp v128, v128, v128 quad_perm:[1,0,3,2] row_mask:0xf bank_mask:0xf
	s_nop 1
; __device__ __forceinline__ float bf_lo(unsigned w) { return __uint_as_float(w << 16); }
; __device__ __forceinline__ float bf_hi(unsigned w) { return __uint_as_float(w & 0xffff0000u); }
; __global__ void __launch_bounds__(NWAVES * 64, 2) trunk_fwd(Args args) {
;     ...
;         else {
;             const f32x4* gr = (const f32x4*)(ARGIN(I_FING) + lane * 8);
;             const f32x4 g0 = gr[0], g1 = gr[1], g2 = gr[128], g3 = gr[129];
;             for (int row0 = gw; row0 < M; row0 += 2 * NGW) {
;                 v4u h0[2], h1[2];
; #pragma unroll
;                 for (int k = 0; k < 2; ++k) { const bf16* hp = HB + (size_t)(row0 + k * NGW) * DM + lane * 8; h0[k] = *(const v4u*)(hp); h1[k] = *(const v4u*)(hp + 512); }
; #pragma unroll
;                 for (int k = 0; k < 2; ++k) { float* op = out + (size_t)(row0 + k * NGW) * DM + lane * 8;
;                     const f32x4 a0 = {bf_lo(h0[k].x), bf_hi(h0[k].x), bf_lo(h0[k].y), bf_hi(h0[k].y)}, a1 = {bf_lo(h0[k].z), bf_hi(h0[k].z), bf_lo(h0[k].w), bf_hi(h0[k].w)};
;                     const f32x4 a2 = {bf_lo(h1[k].x), bf_hi(h1[k].x), bf_lo(h1[k].y), bf_hi(h1[k].y)}, a3 = {bf_lo(h1[k].z), bf_hi(h1[k].z), bf_lo(h1[k].w), bf_hi(h1[k].w)};
;                     float sq = ((a0[0] * a0[0] + a0[1] * a0[1]) + (a0[2] * a0[2] + a0[3] * a0[3])) + ((a1[0] * a1[0] + a1[1] * a1[1]) + (a1[2] * a1[2] + a1[3] * a1[3]))
;                              + ((a2[0] * a2[0] + a2[1] * a2[1]) + (a2[2] * a2[2] + a2[3] * a2[3])) + ((a3[0] * a3[0] + a3[1] * a3[1]) + (a3[2] * a3[2] + a3[3] * a3[3]));
;                     const float r = __builtin_amdgcn_rsqf(wave_sum(sq) * (1.f / DM) + EPS);
;                     *(f32x4*)(op) = a0 * r * g0; *(f32x4*)(op + 4) = a1 * r * g1; *(f32x4*)(op + 512) = a2 * r * g2; *(f32x4*)(op + 516) = a3 * r * g3; }
;             }
	v_add_f32_dpp v128, v128, v128 quad_perm:[2,3,0,1] row_mask:0xf bank_mask:0xf
	s_nop 1
	v_add_f32_dpp v128, v128, v128 row_half_mirror row_mask:0xf bank_mask:0xf
	s_nop 1
	v_add_f32_dpp v128, v128, v128 row_mirror row_mask:0xf bank_mask:0xf
	s_nop 1
	v_readlane_b32 s6, v128, 0
	v_readlane_b32 s7, v128, 16
	v_readlane_b32 s8, v128, 32
	v_readlane_b32 s9, v128, 48
	s_nop 1
	v_mov_b32_e32 v130, s6
	v_add_f32_e32 v130, s7, v130
	v_add_f32_e32 v130, s8, v130
	v_add_f32_e32 v130, s9, v130
	v_fmamk_f32 v130, v130, 0x3a800000, v207
	v_rsq_f32_e32 v130, v130
	s_add_i32 s20, s25, 4096
	s_lshl_b32 s20, s20, 12
	s_mov_b32 s21, 0
	v_lshl_add_u64 v[134:135], v[28:29], 0, s[20:21]
	v_pk_mul_f32 v[96:97], v[96:97], v[130:131] op_sel_hi:[1,0]
	v_pk_mul_f32 v[98:99], v[98:99], v[130:131] op_sel_hi:[1,0]
	v_pk_mul_f32 v[100:101], v[100:101], v[130:131] op_sel_hi:[1,0]
	v_pk_mul_f32 v[102:103], v[102:103], v[130:131] op_sel_hi:[1,0]
	v_pk_mul_f32 v[104:105], v[104:105], v[130:131] op_sel_hi:[1,0]
	v_pk_mul_f32 v[106:107], v[106:107], v[130:131] op_sel_hi:[1,0]
	v_pk_mul_f32 v[108:109], v[108:109], v[130:131] op_sel_hi:[1,0]
	v_pk_mul_f32 v[110:111], v[110:111], v[130:131] op_sel_hi:[1,0]
	v_pk_mul_f32 v[96:97], v[96:97], v[6:7]
	v_pk_mul_f32 v[98:99], v[98:99], v[8:9]
	v_pk_mul_f32 v[100:101], v[100:101], v[2:3]
	v_pk_mul_f32 v[102:103], v[102:103], v[4:5]
	v_pk_mul_f32 v[104:105], v[104:105], v[14:15]
	v_pk_mul_f32 v[106:107], v[106:107], v[16:17]
	v_pk_mul_f32 v[108:109], v[108:109], v[10:11]
	v_pk_mul_f32 v[110:111], v[110:111], v[12:13]
	global_store_dwordx4 v[134:135], v[96:99], off
	global_store_dwordx4 v[134:135], v[100:103], off offset:16
	global_store_dwordx4 v[134:135], v[104:107], off offset:2048
	global_store_dwordx4 v[134:135], v[108:111], off offset:2064
	v_lshlrev_b32_e32 v112, 16, v88
	v_and_b32_e32 v113, 0xffff0000, v88
	v_lshlrev_b32_e32 v114, 16, v89
	v_and_b32_e32 v115, 0xffff0000, v89
	v_lshlrev_b32_e32 v116, 16, v90
	v_and_b32_e32 v117, 0xffff0000, v90
	v_lshlrev_b32_e32 v118, 16, v91
	v_and_b32_e32 v119, 0xffff0000, v91
	v_lshlrev_b32_e32 v120, 16, v92
	v_and_b32_e32 v121, 0xffff0000, v92
	v_lshlrev_b32_e32 v122, 16, v93
	v_and_b32_e32 v123, 0xffff0000, v93
	v_lshlrev_b32_e32 v124, 16, v94
	v_and_b32_e32 v125, 0xffff0000, v94
	v_lshlrev_b32_e32 v126, 16, v95
	v_and_b32_e32 v127, 0xffff0000, v95
	v_pk_mul_f32 v[128:129], v[112:113], v[112:113]
	v_pk_fma_f32 v[128:129], v[114:115], v[114:115], v[128:129]
	v_pk_fma_f32 v[128:129], v[116:117], v[116:117], v[128:129]
	v_pk_fma_f32 v[128:129], v[118:119], v[118:119], v[128:129]
	v_pk_fma_f32 v[128:129], v[120:121], v[120:121], v[128:129]
	v_pk_fma_f32 v[128:129], v[122:123], v[122:123], v[128:129]
	v_pk_fma_f32 v[128:129], v[124:125], v[124:125], v[128:129]
	v_pk_fma_f32 v[128:129], v[126:127], v[126:127], v[128:129]
	v_add_f32_e32 v128, v128, v129
	s_nop 1
	v_add_f32_dpp v128, v128, v128 quad_perm:[1,0,3,2] row_mask:0xf bank_mask:0xf
	s_nop 1
	v_add_f32_dpp v128, v128, v128 quad_perm:[2,3,0,1] row_mask:0xf bank_mask:0xf
	s_nop 1
	v_add_f32_dpp v128, v128, v128 row_half_mirror row_mask:0xf bank_mask:0xf
	s_nop 1
	v_add_f32_dpp v128, v128, v128 row_mirror row_mask:0xf bank_mask:0xf
	s_nop 1
	v_readlane_b32 s6, v128, 0
	v_readlane_b32 s7, v128, 16
	v_readlane_b32 s8, v128, 32
	v_readlane_b32 s9, v128, 48
	s_nop 1
	v_mov_b32_e32 v130, s6
	v_add_f32_e32 v130, s7, v130
	v_add_f32_e32 v130, s8, v130
	v_add_f32_e32 v130, s9, v130
	v_fmamk_f32 v130, v130, 0x3a800000, v207
	v_rsq_f32_e32 v130, v130
	s_add_i32 s20, s25, 6144
	s_lshl_b32 s20, s20, 12
	s_mov_b32 s21, 0
	v_lshl_add_u64 v[134:135], v[28:29], 0, s[20:21]
	v_pk_mul_f32 v[112:113], v[112:113], v[130:131] op_sel_hi:[1,0]
	v_pk_mul_f32 v[114:115], v[114:115], v[130:131] op_sel_hi:[1,0]
	v_pk_mul_f32 v[116:117], v[116:117], v[130:131] op_sel_hi:[1,0]
	v_pk_mul_f32 v[118:119], v[118:119], v[130:131] op_sel_hi:[1,0]
	v_pk_mul_f32 v[120:121], v[120:121], v[130:131] op_sel_hi:[1,0]
	v_pk_mul_f32 v[122:123], v[122:123], v[130:131] op_sel_hi:[1,0]
	v_pk_mul_f32 v[124:125], v[124:125], v[130:131] op_sel_hi:[1,0]
	v_pk_mul_f32 v[126:127], v[126:127], v[130:131] op_sel_hi:[1,0]
	v_pk_mul_f32 v[112:113], v[112:113], v[6:7]
	v_pk_mul_f32 v[114:115], v[114:115], v[8:9]
	v_pk_mul_f32 v[116:117], v[116:117], v[2:3]
	v_pk_mul_f32 v[118:119], v[118:119], v[4:5]
	v_pk_mul_f32 v[120:121], v[120:121], v[14:15]
	v_pk_mul_f32 v[122:123], v[122:123], v[16:17]
	v_pk_mul_f32 v[124:125], v[124:125], v[10:11]
	v_pk_mul_f32 v[126:127], v[126:127], v[12:13]
	global_store_dwordx4 v[134:135], v[112:115], off
	global_store_dwordx4 v[134:135], v[116:119], off offset:16
	global_store_dwordx4 v[134:135], v[120:123], off offset:2048
	global_store_dwordx4 v[134:135], v[124:127], off offset:2064
	s_add_i32 s22, s60, 0x6000
	s_cmp_lt_u32 s22, 0x10000
	s_cbranch_scc0 .Lfin_skipB
	s_add_i32 s20, s22, 0
	s_lshl_b32 s20, s20, 11
	s_mov_b32 s21, 0
	v_lshl_add_u64 v[132:133], v[26:27], 0, s[20:21]
	global_load_dwordx4 v[64:67], v[132:133], off
	global_load_dwordx4 v[68:71], v[132:133], off offset:1024
	s_add_i32 s20, s22, 2048
	s_lshl_b32 s20, s20, 11
	s_mov_b32 s21, 0
	v_lshl_add_u64 v[132:133], v[26:27], 0, s[20:21]
	global_load_dwordx4 v[72:75], v[132:133], off
	global_load_dwordx4 v[76:79], v[132:133], off offset:1024
	s_add_i32 s20, s22, 4096
	s_lshl_b32 s20, s20, 11
	s_mov_b32 s21, 0
	v_lshl_add_u64 v[132:133], v[26:27], 0, s[20:21]
	global_load_dwordx4 v[80:83], v[132:133], off
	global_load_dwordx4 v[84:87], v[132:133], off offset:1024
	s_add_i32 s20, s22, 6144
	s_lshl_b32 s20, s20, 11
	s_mov_b32 s21, 0
	v_lshl_add_u64 v[132:133], v[26:27], 0, s[20:21]
	global_load_dwordx4 v[88:91], v[132:133], off
	global_load_dwordx4 v[92:95], v[132:133], off offset:1024
.Lfin_skipB:
	s_add_i32 s60, s60, 0x4000
	s_cmp_lt_u32 s60, 0x10000
	s_cbranch_scc1 .Lfin_loop
